# gate/up GEMM: first four row-stat quads of EpiSwiglu prefetched under the last MFMA segment of the K loop
# baseline (speedup 1.0000x reference)
; #define PG8_STAGE(bufoff, gbase, voff) do { _Pragma("unroll") for (int _i = 0; _i < 2; ++_i) \
;         __builtin_amdgcn_global_load_lds((const unsigned*)((const char*)(gbase) + (voff)[_i]), (PG8_LAS unsigned*)(lds + (bufoff) + ldsw + _i * 8192), 16, 0, 0); } while (0)
; #define PG8_LDA(dst, b, h) do { _Pragma("unroll") for (int m = 0; m < 4; ++m) _Pragma("unroll") for (int k = 0; k < 2; ++k) dst[m][k] = *(const PG8_LAS bf16x8*)(lds + PG8_SA(b, h) + aoff + m * 2048 + k * 1024); } while (0)
; #define PG8_LDB(dst, b, h) do { _Pragma("unroll") for (int n = 0; n < 2; ++n) _Pragma("unroll") for (int k = 0; k < 2; ++k) dst[n][k] = *(const PG8_LAS bf16x8*)(lds + PG8_SB(b, h) + boff + n * 2048 + k * 1024); } while (0)
; #define PG8_MMA(ai, bj, At, Bt) do { __builtin_amdgcn_s_setprio(1); _Pragma("unroll") for (int m = 0; m < 4; ++m) _Pragma("unroll") for (int n = 0; n < 2; ++n) _Pragma("unroll") for (int k = 0; k < 2; ++k) \
;         acc[ai][bj][m][n] = __builtin_amdgcn_mfma_f32_16x16x32_bf16(Bt[n][k], At[m][k], acc[ai][bj][m][n], 0, 0, 0); __builtin_amdgcn_s_setprio(0); } while (0)
; #define PG8_WAIT_V(n) asm volatile("s_waitcnt vmcnt(" #n ")" ::: "memory")
; #define PG8_WAIT_L(n) asm volatile("s_waitcnt lgkmcnt(" #n ")" ::: "memory")
; #define PG8_BAR __builtin_amdgcn_s_barrier()
; #define PG8_SCHED __builtin_amdgcn_sched_barrier(0)
; template <class Epi, class Sched, bool ALIGN_EPI>
; __device__ __forceinline__ void gemm_phase(PG8_LAS unsigned char* lds, const Gemm g, const Sched& S, const Epi& E) {
;     ...
;         for (int t = 0; t < nt; t += 2) {
;             const bool last = (t == nt - 2);
;             const char* a1 = cA + (size_t)(t + 1) * kstep;
;             const char* a2 = last ? nA : cA + (size_t)(t + 2) * kstep; const char* b2 = last ? nB : cB + (size_t)(t + 2) * kstep;
;             const char* a3 = a2 + kstep; const char* b3 = b2 + kstep;
;             PG8_LDB(B0, 0, 0); PG8_LDB(B1, 0, 1); PG8_SCHED; PG8_LDA(At, 0, 0); PG8_STAGE(PG8_SA(1, 1), a1 + hstepA, voffA);
;             PG8_WAIT_V(8); PG8_WAIT_L(0); PG8_BAR; PG8_MMA(0, 0, At, B0); PG8_MMA(0, 1, At, B1); PG8_BAR; PG8_SCHED;
;             PG8_LDA(At, 0, 1); PG8_STAGE(PG8_SB(0, 0), b2, voffB); PG8_STAGE(PG8_SB(0, 1), b2 + hstepB, voffB); PG8_STAGE(PG8_SA(0, 0), a2, voffA);
;             PG8_WAIT_V(8); PG8_WAIT_L(0); PG8_BAR; PG8_MMA(1, 0, At, B0); PG8_MMA(1, 1, At, B1); PG8_BAR; PG8_SCHED;
.LBB0_369:
	s_add_i32 s61, s26, 2
	s_add_u32 s27, s42, 0xfff80080
	s_addc_u32 s28, s43, -1
	s_add_i32 s88, 0, 0x10000
	s_cmp_eq_u32 s54, s26
	s_cselect_b32 s29, s2, s28
	s_cselect_b32 s28, s3, s27
	s_cselect_b32 s27, s17, s60
	s_cselect_b32 s26, s19, s59
	s_cselect_b32 s91, 1, 0
	s_add_i32 s90, 0, 0x14000
	v_add_u32_e32 v142, s88, v179
	v_add_u32_e32 v170, s90, v179
	ds_read_b128 v[130:133], v142
	ds_read_b128 v[134:137], v142 offset:1024
	ds_read_b128 v[138:141], v142 offset:2048
	ds_read_b128 v[142:145], v142 offset:3072
	ds_read_b128 v[146:149], v170
	ds_read_b128 v[162:165], v170 offset:1024
	ds_read_b128 v[166:169], v170 offset:2048
	ds_read_b128 v[170:173], v170 offset:3072
	v_lshl_add_u64 v[210:211], s[42:43], 0, v[158:159]
	s_add_i32 m0, s25, 0xc000
	ds_read_b128 v[174:177], v180
	ds_read_b128 v[182:185], v180 offset:1024
	ds_read_b128 v[186:189], v180 offset:2048
	ds_read_b128 v[190:193], v180 offset:3072
	ds_read_b128 v[194:197], v180 offset:4096
	ds_read_b128 v[198:201], v180 offset:5120
	ds_read_b128 v[202:205], v180 offset:6144
	ds_read_b128 v[206:209], v180 offset:7168
	global_load_lds_dwordx4 v[210:211], off
	v_lshl_add_u64 v[210:211], s[42:43], 0, v[160:161]
	s_add_i32 m0, s25, 0xe000
	s_nop 0
	global_load_lds_dwordx4 v[210:211], off
	s_waitcnt vmcnt(8)
	s_waitcnt lgkmcnt(0)
	s_barrier
	s_setprio 1
	s_waitcnt lgkmcnt(0)
	v_mfma_f32_16x16x32_bf16 v[126:129], v[130:133], v[174:177], v[126:129]
	v_mfma_f32_16x16x32_bf16 v[118:121], v[138:141], v[174:177], v[118:121]
	v_mfma_f32_16x16x32_bf16 v[110:113], v[130:133], v[186:189], v[110:113]
	v_mfma_f32_16x16x32_bf16 v[102:105], v[138:141], v[186:189], v[102:105]
	v_mfma_f32_16x16x32_bf16 v[94:97], v[130:133], v[194:197], v[94:97]
	v_mfma_f32_16x16x32_bf16 v[86:89], v[138:141], v[194:197], v[86:89]
	v_mfma_f32_16x16x32_bf16 v[78:81], v[130:133], v[202:205], v[78:81]
	v_mfma_f32_16x16x32_bf16 v[70:73], v[138:141], v[202:205], v[70:73]
	v_mfma_f32_16x16x32_bf16 v[126:129], v[134:137], v[182:185], v[126:129]
	v_mfma_f32_16x16x32_bf16 v[118:121], v[142:145], v[182:185], v[118:121]
	v_mfma_f32_16x16x32_bf16 v[110:113], v[134:137], v[190:193], v[110:113]
	v_mfma_f32_16x16x32_bf16 v[102:105], v[142:145], v[190:193], v[102:105]
	v_mfma_f32_16x16x32_bf16 v[94:97], v[134:137], v[198:201], v[94:97]
	v_mfma_f32_16x16x32_bf16 v[86:89], v[142:145], v[198:201], v[86:89]
	v_mfma_f32_16x16x32_bf16 v[78:81], v[134:137], v[206:209], v[78:81]
	v_mfma_f32_16x16x32_bf16 v[70:73], v[142:145], v[206:209], v[70:73]
	s_setprio 0
	s_setprio 1
	v_mfma_f32_16x16x32_bf16 v[122:125], v[146:149], v[174:177], v[122:125]
	v_mfma_f32_16x16x32_bf16 v[114:117], v[166:169], v[174:177], v[114:117]
	v_mfma_f32_16x16x32_bf16 v[106:109], v[146:149], v[186:189], v[106:109]
	v_mfma_f32_16x16x32_bf16 v[98:101], v[166:169], v[186:189], v[98:101]
	v_mfma_f32_16x16x32_bf16 v[90:93], v[146:149], v[194:197], v[90:93]
	v_mfma_f32_16x16x32_bf16 v[82:85], v[166:169], v[194:197], v[82:85]
	v_mfma_f32_16x16x32_bf16 v[74:77], v[146:149], v[202:205], v[74:77]
	v_mfma_f32_16x16x32_bf16 v[66:69], v[166:169], v[202:205], v[66:69]
	v_mfma_f32_16x16x32_bf16 v[122:125], v[162:165], v[182:185], v[122:125]
	v_mfma_f32_16x16x32_bf16 v[114:117], v[170:173], v[182:185], v[114:117]
	v_mfma_f32_16x16x32_bf16 v[106:109], v[162:165], v[190:193], v[106:109]
	v_mfma_f32_16x16x32_bf16 v[98:101], v[170:173], v[190:193], v[98:101]
	v_mfma_f32_16x16x32_bf16 v[90:93], v[162:165], v[198:201], v[90:93]
	v_mfma_f32_16x16x32_bf16 v[82:85], v[170:173], v[198:201], v[82:85]
	v_mfma_f32_16x16x32_bf16 v[74:77], v[162:165], v[206:209], v[74:77]
	v_mfma_f32_16x16x32_bf16 v[66:69], v[170:173], v[206:209], v[66:69]
	s_setprio 0
	s_barrier
	s_add_i32 s88, s88, s44
	v_lshl_add_u64 v[210:211], s[26:27], 0, v[0:1]
	s_mov_b32 m0, s88
	ds_read_b128 v[174:177], v180 offset:16384
	ds_read_b128 v[182:185], v180 offset:17408
	ds_read_b128 v[186:189], v180 offset:18432
	ds_read_b128 v[190:193], v180 offset:19456
	ds_read_b128 v[194:197], v180 offset:20480
	ds_read_b128 v[198:201], v180 offset:21504
	ds_read_b128 v[202:205], v180 offset:22528
	ds_read_b128 v[206:209], v180 offset:23552
	global_load_lds_dwordx4 v[210:211], off
	s_add_i32 m0, s88, 0x2000
	s_add_u32 s88, s26, 0x40000
	v_lshl_add_u64 v[212:213], s[26:27], 0, v[150:151]
	s_addc_u32 s89, s27, 0
	s_add_i32 s90, s90, s44
	global_load_lds_dwordx4 v[212:213], off
	v_lshl_add_u64 v[214:215], s[88:89], 0, v[0:1]
	s_mov_b32 m0, s90
	v_lshl_add_u64 v[216:217], s[28:29], 0, v[152:153]
	global_load_lds_dwordx4 v[214:215], off
	v_lshl_add_u64 v[214:215], s[88:89], 0, v[150:151]
	s_add_i32 m0, s90, 0x2000
	s_nop 0
	global_load_lds_dwordx4 v[214:215], off
	v_lshl_add_u64 v[214:215], s[28:29], 0, v[154:155]
	s_mov_b32 m0, s25
	s_nop 0
	global_load_lds_dwordx4 v[214:215], off
	s_mov_b32 m0, s46
	s_nop 0
	global_load_lds_dwordx4 v[216:217], off
	s_waitcnt vmcnt(8)
	s_waitcnt lgkmcnt(0)
	s_barrier
; #define PG8_STAGE(bufoff, gbase, voff) do { _Pragma("unroll") for (int _i = 0; _i < 2; ++_i) \
;         __builtin_amdgcn_global_load_lds((const unsigned*)((const char*)(gbase) + (voff)[_i]), (PG8_LAS unsigned*)(lds + (bufoff) + ldsw + _i * 8192), 16, 0, 0); } while (0)
; #define PG8_LDA(dst, b, h) do { _Pragma("unroll") for (int m = 0; m < 4; ++m) _Pragma("unroll") for (int k = 0; k < 2; ++k) dst[m][k] = *(const PG8_LAS bf16x8*)(lds + PG8_SA(b, h) + aoff + m * 2048 + k * 1024); } while (0)
; #define PG8_LDB(dst, b, h) do { _Pragma("unroll") for (int n = 0; n < 2; ++n) _Pragma("unroll") for (int k = 0; k < 2; ++k) dst[n][k] = *(const PG8_LAS bf16x8*)(lds + PG8_SB(b, h) + boff + n * 2048 + k * 1024); } while (0)
; #define PG8_MMA(ai, bj, At, Bt) do { __builtin_amdgcn_s_setprio(1); _Pragma("unroll") for (int m = 0; m < 4; ++m) _Pragma("unroll") for (int n = 0; n < 2; ++n) _Pragma("unroll") for (int k = 0; k < 2; ++k) \
;         acc[ai][bj][m][n] = __builtin_amdgcn_mfma_f32_16x16x32_bf16(Bt[n][k], At[m][k], acc[ai][bj][m][n], 0, 0, 0); __builtin_amdgcn_s_setprio(0); } while (0)
; #define PG8_WAIT_V(n) asm volatile("s_waitcnt vmcnt(" #n ")" ::: "memory")
; template <class Epi, class Sched, bool ALIGN_EPI>
; __device__ __forceinline__ void gemm_phase(PG8_LAS unsigned char* lds, const Gemm g, const Sched& S, const Epi& E) {
;     ...
;             PG8_LDB(B0, 0, 0); PG8_LDB(B1, 0, 1); PG8_SCHED; PG8_LDA(At, 0, 0); PG8_STAGE(PG8_SA(1, 1), a1 + hstepA, voffA);
;             PG8_WAIT_V(8); PG8_WAIT_L(0); PG8_BAR; PG8_MMA(0, 0, At, B0); PG8_MMA(0, 1, At, B1); PG8_BAR; PG8_SCHED;
;             PG8_LDA(At, 0, 1); PG8_STAGE(PG8_SB(0, 0), b2, voffB); PG8_STAGE(PG8_SB(0, 1), b2 + hstepB, voffB); PG8_STAGE(PG8_SA(0, 0), a2, voffA);
;             PG8_WAIT_V(8); PG8_WAIT_L(0); PG8_BAR; PG8_MMA(1, 0, At, B0); PG8_MMA(1, 1, At, B1); PG8_BAR; PG8_SCHED;
;             PG8_LDB(B0, 1, 0); PG8_LDB(B1, 1, 1); PG8_SCHED; PG8_LDA(At, 1, 0); PG8_STAGE(PG8_SA(0, 1), a2 + hstepA, voffA);
;             PG8_WAIT_V(8); PG8_WAIT_L(0); PG8_BAR; PG8_MMA(0, 0, At, B0); PG8_MMA(0, 1, At, B1); PG8_BAR; PG8_SCHED;
;             PG8_LDA(At, 1, 1); PG8_STAGE(PG8_SB(1, 0), b3, voffB); PG8_STAGE(PG8_SB(1, 1), b3 + hstepB, voffB); PG8_STAGE(PG8_SA(1, 0), a3, voffA);
;             PG8_WAIT_V(8); PG8_WAIT_L(0); PG8_BAR; PG8_MMA(1, 0, At, B0); PG8_MMA(1, 1, At, B1); PG8_BAR; PG8_SCHED;
	s_setprio 1
	s_waitcnt lgkmcnt(0)
	v_mfma_f32_16x16x32_bf16 v[62:65], v[130:133], v[174:177], v[62:65]
	v_mfma_f32_16x16x32_bf16 v[54:57], v[138:141], v[174:177], v[54:57]
	v_mfma_f32_16x16x32_bf16 v[46:49], v[130:133], v[186:189], v[46:49]
	v_mfma_f32_16x16x32_bf16 v[38:41], v[138:141], v[186:189], v[38:41]
	v_mfma_f32_16x16x32_bf16 v[30:33], v[130:133], v[194:197], v[30:33]
	v_mfma_f32_16x16x32_bf16 v[22:25], v[138:141], v[194:197], v[22:25]
	v_mfma_f32_16x16x32_bf16 v[14:17], v[130:133], v[202:205], v[14:17]
	v_mfma_f32_16x16x32_bf16 v[6:9], v[138:141], v[202:205], v[6:9]
	v_mfma_f32_16x16x32_bf16 v[62:65], v[134:137], v[182:185], v[62:65]
	v_mfma_f32_16x16x32_bf16 v[54:57], v[142:145], v[182:185], v[54:57]
	v_mfma_f32_16x16x32_bf16 v[46:49], v[134:137], v[190:193], v[46:49]
	v_mfma_f32_16x16x32_bf16 v[38:41], v[142:145], v[190:193], v[38:41]
	v_mfma_f32_16x16x32_bf16 v[30:33], v[134:137], v[198:201], v[30:33]
	v_mfma_f32_16x16x32_bf16 v[22:25], v[142:145], v[198:201], v[22:25]
	v_mfma_f32_16x16x32_bf16 v[14:17], v[134:137], v[206:209], v[14:17]
	v_mfma_f32_16x16x32_bf16 v[6:9], v[142:145], v[206:209], v[6:9]
	s_setprio 0
	s_setprio 1
	v_mfma_f32_16x16x32_bf16 v[58:61], v[146:149], v[174:177], v[58:61]
	v_mfma_f32_16x16x32_bf16 v[50:53], v[166:169], v[174:177], v[50:53]
	v_mfma_f32_16x16x32_bf16 v[42:45], v[146:149], v[186:189], v[42:45]
	v_mfma_f32_16x16x32_bf16 v[34:37], v[166:169], v[186:189], v[34:37]
	v_mfma_f32_16x16x32_bf16 v[26:29], v[146:149], v[194:197], v[26:29]
	v_mfma_f32_16x16x32_bf16 v[18:21], v[166:169], v[194:197], v[18:21]
	v_mfma_f32_16x16x32_bf16 v[10:13], v[146:149], v[202:205], v[10:13]
	v_mfma_f32_16x16x32_bf16 v[2:5], v[166:169], v[202:205], v[2:5]
	v_mfma_f32_16x16x32_bf16 v[58:61], v[162:165], v[182:185], v[58:61]
	v_mfma_f32_16x16x32_bf16 v[50:53], v[170:173], v[182:185], v[50:53]
	v_mfma_f32_16x16x32_bf16 v[42:45], v[162:165], v[190:193], v[42:45]
	v_mfma_f32_16x16x32_bf16 v[34:37], v[170:173], v[190:193], v[34:37]
	v_mfma_f32_16x16x32_bf16 v[26:29], v[162:165], v[198:201], v[26:29]
	v_mfma_f32_16x16x32_bf16 v[18:21], v[170:173], v[198:201], v[18:21]
	v_mfma_f32_16x16x32_bf16 v[10:13], v[162:165], v[206:209], v[10:13]
	v_mfma_f32_16x16x32_bf16 v[2:5], v[170:173], v[206:209], v[2:5]
	s_setprio 0
	s_barrier
	s_add_i32 s88, 0, 0x18000
	s_add_i32 s89, 0, 0x1c000
	v_add_u32_e32 v142, s88, v179
	v_add_u32_e32 v170, s89, v179
	ds_read_b128 v[130:133], v142
	ds_read_b128 v[134:137], v142 offset:1024
	ds_read_b128 v[138:141], v142 offset:2048
	ds_read_b128 v[142:145], v142 offset:3072
	ds_read_b128 v[146:149], v170
	ds_read_b128 v[162:165], v170 offset:1024
	ds_read_b128 v[166:169], v170 offset:2048
	ds_read_b128 v[170:173], v170 offset:3072
	s_add_u32 s28, s28, 0x80000
	s_addc_u32 s29, s29, 0
	s_mov_b32 m0, s47
	v_lshl_add_u64 v[218:219], s[28:29], 0, v[154:155]
	ds_read_b128 v[174:177], v180 offset:32768
	ds_read_b128 v[182:185], v180 offset:33792
	ds_read_b128 v[186:189], v180 offset:34816
	ds_read_b128 v[190:193], v180 offset:35840
	ds_read_b128 v[194:197], v180 offset:36864
	ds_read_b128 v[198:201], v180 offset:37888
	ds_read_b128 v[202:205], v180 offset:38912
	ds_read_b128 v[206:209], v180 offset:39936
	global_load_lds_dwordx4 v[218:219], off
	v_lshl_add_u64 v[218:219], s[28:29], 0, v[152:153]
	s_mov_b32 m0, s48
	s_nop 0
	global_load_lds_dwordx4 v[218:219], off
	s_waitcnt vmcnt(8)
	s_waitcnt lgkmcnt(0)
	s_barrier
	s_setprio 1
	s_waitcnt lgkmcnt(0)
	v_mfma_f32_16x16x32_bf16 v[126:129], v[130:133], v[174:177], v[126:129]
	v_mfma_f32_16x16x32_bf16 v[118:121], v[138:141], v[174:177], v[118:121]
	v_mfma_f32_16x16x32_bf16 v[110:113], v[130:133], v[186:189], v[110:113]
	v_mfma_f32_16x16x32_bf16 v[102:105], v[138:141], v[186:189], v[102:105]
	v_mfma_f32_16x16x32_bf16 v[94:97], v[130:133], v[194:197], v[94:97]
	v_mfma_f32_16x16x32_bf16 v[86:89], v[138:141], v[194:197], v[86:89]
	v_mfma_f32_16x16x32_bf16 v[78:81], v[130:133], v[202:205], v[78:81]
	v_mfma_f32_16x16x32_bf16 v[70:73], v[138:141], v[202:205], v[70:73]
	v_mfma_f32_16x16x32_bf16 v[126:129], v[134:137], v[182:185], v[126:129]
	v_mfma_f32_16x16x32_bf16 v[118:121], v[142:145], v[182:185], v[118:121]
	v_mfma_f32_16x16x32_bf16 v[110:113], v[134:137], v[190:193], v[110:113]
	v_mfma_f32_16x16x32_bf16 v[102:105], v[142:145], v[190:193], v[102:105]
	v_mfma_f32_16x16x32_bf16 v[94:97], v[134:137], v[198:201], v[94:97]
	v_mfma_f32_16x16x32_bf16 v[86:89], v[142:145], v[198:201], v[86:89]
	v_mfma_f32_16x16x32_bf16 v[78:81], v[134:137], v[206:209], v[78:81]
	v_mfma_f32_16x16x32_bf16 v[70:73], v[142:145], v[206:209], v[70:73]
	s_setprio 0
	s_setprio 1
	v_mfma_f32_16x16x32_bf16 v[122:125], v[146:149], v[174:177], v[122:125]
	v_mfma_f32_16x16x32_bf16 v[114:117], v[166:169], v[174:177], v[114:117]
	v_mfma_f32_16x16x32_bf16 v[106:109], v[146:149], v[186:189], v[106:109]
	v_mfma_f32_16x16x32_bf16 v[98:101], v[166:169], v[186:189], v[98:101]
	v_mfma_f32_16x16x32_bf16 v[90:93], v[146:149], v[194:197], v[90:93]
	v_mfma_f32_16x16x32_bf16 v[82:85], v[166:169], v[194:197], v[82:85]
	v_mfma_f32_16x16x32_bf16 v[74:77], v[146:149], v[202:205], v[74:77]
	v_mfma_f32_16x16x32_bf16 v[66:69], v[166:169], v[202:205], v[66:69]
	v_mfma_f32_16x16x32_bf16 v[122:125], v[162:165], v[182:185], v[122:125]
	v_mfma_f32_16x16x32_bf16 v[114:117], v[170:173], v[182:185], v[114:117]
	v_mfma_f32_16x16x32_bf16 v[106:109], v[162:165], v[190:193], v[106:109]
	v_mfma_f32_16x16x32_bf16 v[98:101], v[170:173], v[190:193], v[98:101]
	v_mfma_f32_16x16x32_bf16 v[90:93], v[162:165], v[198:201], v[90:93]
	v_mfma_f32_16x16x32_bf16 v[82:85], v[170:173], v[198:201], v[82:85]
	v_mfma_f32_16x16x32_bf16 v[74:77], v[162:165], v[206:209], v[74:77]
	v_mfma_f32_16x16x32_bf16 v[66:69], v[170:173], v[206:209], v[66:69]
	s_setprio 0
	s_barrier
; #define PG8_STAGE(bufoff, gbase, voff) do { _Pragma("unroll") for (int _i = 0; _i < 2; ++_i) \
;         __builtin_amdgcn_global_load_lds((const unsigned*)((const char*)(gbase) + (voff)[_i]), (PG8_LAS unsigned*)(lds + (bufoff) + ldsw + _i * 8192), 16, 0, 0); } while (0)
; #define PG8_LDA(dst, b, h) do { _Pragma("unroll") for (int m = 0; m < 4; ++m) _Pragma("unroll") for (int k = 0; k < 2; ++k) dst[m][k] = *(const PG8_LAS bf16x8*)(lds + PG8_SA(b, h) + aoff + m * 2048 + k * 1024); } while (0)
; #define PG8_MMA(ai, bj, At, Bt) do { __builtin_amdgcn_s_setprio(1); _Pragma("unroll") for (int m = 0; m < 4; ++m) _Pragma("unroll") for (int n = 0; n < 2; ++n) _Pragma("unroll") for (int k = 0; k < 2; ++k) \
;         acc[ai][bj][m][n] = __builtin_amdgcn_mfma_f32_16x16x32_bf16(Bt[n][k], At[m][k], acc[ai][bj][m][n], 0, 0, 0); __builtin_amdgcn_s_setprio(0); } while (0)
; #define PG8_WAIT_V(n) asm volatile("s_waitcnt vmcnt(" #n ")" ::: "memory")
; #define PG8_WAIT_L(n) asm volatile("s_waitcnt lgkmcnt(" #n ")" ::: "memory")
; #define PG8_BAR __builtin_amdgcn_s_barrier()
; #define PG8_SCHED __builtin_amdgcn_sched_barrier(0)
; template <class Epi, class Sched, bool ALIGN_EPI>
; __device__ __forceinline__ void gemm_phase(PG8_LAS unsigned char* lds, const Gemm g, const Sched& S, const Epi& E) {
;     ...
;             PG8_LDA(At, 1, 1); PG8_STAGE(PG8_SB(1, 0), b3, voffB); PG8_STAGE(PG8_SB(1, 1), b3 + hstepB, voffB); PG8_STAGE(PG8_SA(1, 0), a3, voffA);
;             PG8_WAIT_V(8); PG8_WAIT_L(0); PG8_BAR; PG8_MMA(1, 0, At, B0); PG8_MMA(1, 1, At, B1); PG8_BAR; PG8_SCHED;
;     __device__ __forceinline__ void operator()(const f32x4 (&acc)[2][2][4][2], const pg8::Unit& u, int wr, int wc, int fr, int fq) const {
;     ...
;             for (int m = 0; m < 4; ++m) rq[ai][m] = *(const f32x4*)(rowss + (size_t)(row0 + ai * 128 + m * 16) * 16 + 4 * fq);
	s_add_i32 s28, s88, s44
	v_lshl_add_u64 v[210:211], v[210:211], 0, s[80:81]
	s_mov_b32 m0, s28
	ds_read_b128 v[174:177], v180 offset:49152
	ds_read_b128 v[182:185], v180 offset:50176
	ds_read_b128 v[186:189], v180 offset:51200
	ds_read_b128 v[190:193], v180 offset:52224
	ds_read_b128 v[194:197], v180 offset:53248
	ds_read_b128 v[198:201], v180 offset:54272
	ds_read_b128 v[202:205], v180 offset:55296
	ds_read_b128 v[206:209], v180 offset:56320
	global_load_lds_dwordx4 v[210:211], off
	s_add_i32 m0, s28, 0x2000
	s_add_u32 s26, s26, 0x40080
	v_lshl_add_u64 v[210:211], v[212:213], 0, s[80:81]
	s_addc_u32 s27, s27, 0
	s_add_i32 s28, s89, s44
	global_load_lds_dwordx4 v[210:211], off
	v_lshl_add_u64 v[210:211], s[26:27], 0, v[0:1]
	s_mov_b32 m0, s28
	s_nop 0
	global_load_lds_dwordx4 v[210:211], off
	v_lshl_add_u64 v[210:211], s[26:27], 0, v[150:151]
	s_add_i32 m0, s28, 0x2000
	s_nop 0
	global_load_lds_dwordx4 v[210:211], off
	v_lshl_add_u64 v[210:211], v[214:215], 0, s[80:81]
	s_mov_b32 m0, s50
	s_nop 0
	global_load_lds_dwordx4 v[210:211], off
	v_lshl_add_u64 v[210:211], v[216:217], 0, s[80:81]
	s_mov_b32 m0, s51
	s_nop 0
	global_load_lds_dwordx4 v[210:211], off
	s_waitcnt vmcnt(8)
	s_cmp_eq_u32 s91, 0
	s_cbranch_scc1 .Lgu_nopf
	v_lshl_add_u32 v238, s24, 8, v178
	v_ashrrev_i32_e32 v239, 31, v238
	v_lshlrev_b64 v[236:237], 6, v[238:239]
	v_lshl_add_u64 v[236:237], v[156:157], 0, v[236:237]
	global_load_dwordx4 v[220:223], v[236:237], off
	global_load_dwordx4 v[224:227], v[236:237], off offset:1024
	global_load_dwordx4 v[228:231], v[236:237], off offset:2048
	global_load_dwordx4 v[232:235], v[236:237], off offset:3072
.Lgu_nopf:
	s_waitcnt lgkmcnt(0)
	s_barrier
	s_setprio 1
	s_waitcnt lgkmcnt(0)
	v_mfma_f32_16x16x32_bf16 v[62:65], v[130:133], v[174:177], v[62:65]
	v_mfma_f32_16x16x32_bf16 v[54:57], v[138:141], v[174:177], v[54:57]
	v_mfma_f32_16x16x32_bf16 v[46:49], v[130:133], v[186:189], v[46:49]
	v_mfma_f32_16x16x32_bf16 v[38:41], v[138:141], v[186:189], v[38:41]
	v_mfma_f32_16x16x32_bf16 v[30:33], v[130:133], v[194:197], v[30:33]
	v_mfma_f32_16x16x32_bf16 v[22:25], v[138:141], v[194:197], v[22:25]
	v_mfma_f32_16x16x32_bf16 v[14:17], v[130:133], v[202:205], v[14:17]
	v_mfma_f32_16x16x32_bf16 v[6:9], v[138:141], v[202:205], v[6:9]
	v_mfma_f32_16x16x32_bf16 v[62:65], v[134:137], v[182:185], v[62:65]
	v_mfma_f32_16x16x32_bf16 v[54:57], v[142:145], v[182:185], v[54:57]
	v_mfma_f32_16x16x32_bf16 v[46:49], v[134:137], v[190:193], v[46:49]
	v_mfma_f32_16x16x32_bf16 v[38:41], v[142:145], v[190:193], v[38:41]
	v_mfma_f32_16x16x32_bf16 v[30:33], v[134:137], v[198:201], v[30:33]
	v_mfma_f32_16x16x32_bf16 v[22:25], v[142:145], v[198:201], v[22:25]
	v_mfma_f32_16x16x32_bf16 v[14:17], v[134:137], v[206:209], v[14:17]
	v_mfma_f32_16x16x32_bf16 v[6:9], v[142:145], v[206:209], v[6:9]
	s_setprio 0
	s_setprio 1
	v_mfma_f32_16x16x32_bf16 v[58:61], v[146:149], v[174:177], v[58:61]
	v_mfma_f32_16x16x32_bf16 v[50:53], v[166:169], v[174:177], v[50:53]
	v_mfma_f32_16x16x32_bf16 v[42:45], v[146:149], v[186:189], v[42:45]
	v_mfma_f32_16x16x32_bf16 v[34:37], v[166:169], v[186:189], v[34:37]
	v_mfma_f32_16x16x32_bf16 v[26:29], v[146:149], v[194:197], v[26:29]
	v_mfma_f32_16x16x32_bf16 v[18:21], v[166:169], v[194:197], v[18:21]
	v_mfma_f32_16x16x32_bf16 v[10:13], v[146:149], v[202:205], v[10:13]
	v_mfma_f32_16x16x32_bf16 v[2:5], v[166:169], v[202:205], v[2:5]
	v_mfma_f32_16x16x32_bf16 v[58:61], v[162:165], v[182:185], v[58:61]
	v_mfma_f32_16x16x32_bf16 v[50:53], v[170:173], v[182:185], v[50:53]
	v_mfma_f32_16x16x32_bf16 v[42:45], v[162:165], v[190:193], v[42:45]
	v_mfma_f32_16x16x32_bf16 v[34:37], v[170:173], v[190:193], v[34:37]
	v_mfma_f32_16x16x32_bf16 v[26:29], v[162:165], v[198:201], v[26:29]
	v_mfma_f32_16x16x32_bf16 v[18:21], v[170:173], v[198:201], v[18:21]
	v_mfma_f32_16x16x32_bf16 v[10:13], v[162:165], v[206:209], v[10:13]
	v_mfma_f32_16x16x32_bf16 v[2:5], v[170:173], v[206:209], v[2:5]
	s_setprio 0
	s_barrier
	s_add_u32 s42, s42, 0x100
	s_addc_u32 s43, s43, 0
	s_add_u32 s59, s59, 0x100
	s_addc_u32 s60, s60, 0
	s_cmp_ge_i32 s61, s49
	s_mov_b32 s26, s61
	s_cbranch_scc0 .LBB0_369

; __device__ __forceinline__ float silu_f(float x) { return x * __builtin_amdgcn_rcpf(1.f + __expf(-x)); }
; __device__ __forceinline__ float sum4q(const f32x4 a) { return (a[0] + a[1]) + (a[2] + a[3]); }
;     __device__ __forceinline__ void operator()(const f32x4 (&acc)[2][2][4][2], const pg8::Unit& u, int wr, int wc, int fr, int fq) const {
;         const int row0 = u.pm * 256 + wr * 64 + fr, col0 = u.pn * 128 + wc * 32 + 8 * fq;
;         f32x4 rq[2][4];
; #pragma unroll
;         for (int ai = 0; ai < 2; ++ai)
; #pragma unroll
;             for (int m = 0; m < 4; ++m) rq[ai][m] = *(const f32x4*)(rowss + (size_t)(row0 + ai * 128 + m * 16) * 16 + 4 * fq);
; #pragma unroll
;         for (int ai = 0; ai < 2; ++ai)
; #pragma unroll
;             for (int m = 0; m < 4; ++m) {
;                 const int row = row0 + ai * 128 + m * 16;
;                 float ssq = sum4q(rq[ai][m]); ssq += __shfl_xor(ssq, 16); ssq += __shfl_xor(ssq, 32);
;                 const float r = rsqrtf(ssq * (1.f / DM) + EPS);
;                 float h[8];
; #pragma unroll
;                 for (int n = 0; n < 2; ++n)
; #pragma unroll
;                     for (int i = 0; i < 4; ++i) h[4 * n + i] = silu_f(acc[ai][0][m][n][i] * r) * (acc[ai][1][m][n][i] * r);
.LBB0_372:
	v_lshl_add_u32 v138, s24, 8, v178
	v_or_b32_e32 v174, 16, v138
	v_ashrrev_i32_e32 v139, 31, v138
	v_ashrrev_i32_e32 v175, 31, v174
	v_lshlrev_b64 v[130:131], 6, v[138:139]
	v_lshlrev_b64 v[134:135], 6, v[174:175]
	v_lshl_add_u64 v[130:131], v[156:157], 0, v[130:131]
	v_lshl_add_u64 v[134:135], v[156:157], 0, v[134:135]
	s_nop 0
	v_and_b32_e32 v140, 64, v247
	s_nop 0
	v_xor_b32_e32 v139, 16, v247
	v_add_u32_e32 v140, 64, v140
	v_xor_b32_e32 v141, 32, v247
	v_cmp_lt_i32_e32 vcc, v139, v140
	v_add_u32_e32 v164, 0xa0, v138
	v_add_u32_e32 v162, 0xb0, v138
	v_cndmask_b32_e32 v182, v247, v139, vcc
	v_cmp_lt_i32_e32 vcc, v141, v140
	v_ashrrev_i32_e32 v165, 31, v164
	v_ashrrev_i32_e32 v163, 31, v162
	v_cndmask_b32_e32 v183, v247, v141, vcc
	v_or_b32_e32 v176, 32, v138
	v_lshlrev_b64 v[146:147], 6, v[164:165]
	v_lshlrev_b64 v[148:149], 6, v[162:163]
	v_lshlrev_b32_e32 v165, 2, v182
	v_lshlrev_b32_e32 v163, 2, v183
	v_lshl_or_b32 v175, s58, 8, v181
	v_or_b32_e32 v172, 48, v138
	v_add_u32_e32 v170, 0x80, v138
	v_add_u32_e32 v168, 0x90, v138
	v_lshlrev_b32_e32 v138, 13, v138
	v_ashrrev_i32_e32 v177, 31, v176
	v_ashrrev_i32_e32 v173, 31, v172
	v_add3_u32 v184, s70, v138, v175
	v_lshlrev_b64 v[138:139], 6, v[176:177]
	v_ashrrev_i32_e32 v169, 31, v168
	v_lshlrev_b64 v[140:141], 6, v[172:173]
	v_lshlrev_b64 v[144:145], 6, v[168:169]
	v_subrev_u32_e32 v169, s66, v184
	v_lshl_add_u64 v[186:187], v[156:157], 0, v[146:147]
	v_lshl_add_u64 v[188:189], v[156:157], 0, v[148:149]
	s_mov_b32 s2, 0x358637bd
	v_mov_b64_e32 v[166:167], s[2:3]
	s_mov_b32 s2, 0x3a800000
	v_ashrrev_i32_e32 v171, 31, v170
	v_lshlrev_b64 v[142:143], 6, v[170:171]
	s_mov_b32 s58, s62
	s_mov_b32 s59, s63
	s_waitcnt vmcnt(0)
	v_mov_b32_e32 v130, v220
	v_mov_b32_e32 v131, v221
	v_mov_b32_e32 v132, v222
	v_mov_b32_e32 v133, v223
	v_mov_b32_e32 v134, v224
	v_mov_b32_e32 v135, v225
	v_mov_b32_e32 v136, v226
	v_mov_b32_e32 v137, v227
	v_mov_b32_e32 v182, v131
	v_mov_b32_e32 v183, v132
	v_mov_b32_e32 v131, v133
	v_mov_b32_e32 v132, v135
	v_mov_b32_e32 v133, v136
	v_mov_b32_e32 v135, v137
	v_pk_add_f32 v[130:131], v[182:183], v[130:131]
	v_pk_add_f32 v[132:133], v[132:133], v[134:135]
	v_mov_b32_e32 v135, v130
	v_mov_b32_e32 v134, v132
	v_mov_b32_e32 v130, v133
	v_pk_add_f32 v[130:131], v[134:135], v[130:131]
	v_lshl_add_u64 v[134:135], v[156:157], 0, v[138:139]
	v_lshl_add_u64 v[136:137], v[156:157], 0, v[140:141]
	v_mov_b32_e32 v182, v228
	v_mov_b32_e32 v183, v229
	v_mov_b32_e32 v184, v230
	v_mov_b32_e32 v185, v231
	v_mov_b32_e32 v146, v232
	v_mov_b32_e32 v147, v233
	v_mov_b32_e32 v148, v234
	v_mov_b32_e32 v149, v235
	ds_bpermute_b32 v133, v165, v131
	ds_bpermute_b32 v132, v165, v130
	v_lshl_add_u64 v[138:139], v[156:157], 0, v[142:143]
	v_lshl_add_u64 v[140:141], v[156:157], 0, v[144:145]
	s_waitcnt lgkmcnt(0)
	v_pk_add_f32 v[130:131], v[130:131], v[132:133]
	ds_bpermute_b32 v133, v163, v131
	ds_bpermute_b32 v132, v163, v130
	s_waitcnt lgkmcnt(0)
	v_pk_add_f32 v[130:131], v[130:131], v[132:133]
	s_nop 0
	v_pk_fma_f32 v[190:191], v[130:131], s[2:3], v[166:167] op_sel_hi:[1,0,0]
	s_nop 0
	v_mul_f32_e32 v130, 0x4b800000, v191
	v_cmp_gt_f32_e32 vcc, s83, v191
	s_nop 1
	v_cndmask_b32_e32 v130, v191, v130, vcc
	v_rsq_f32_e32 v171, v130
	global_load_dwordx4 v[142:145], v[138:139], off
	s_nop 0
	global_load_dwordx4 v[138:141], v[140:141], off
	s_nop 0
	global_load_dwordx4 v[134:137], v[186:187], off
	global_load_dwordx4 v[130:133], v[188:189], off
	v_mul_f32_e32 v173, 0x45800000, v171
	v_cndmask_b32_e32 v186, v171, v173, vcc
	v_pk_mul_f32 v[118:119], v[118:119], v[186:187] op_sel_hi:[1,0]
	v_pk_mul_f32 v[120:121], v[120:121], v[186:187] op_sel_hi:[1,0]
	v_mul_f32_e32 v188, 0xbfb8aa3b, v118
	v_mul_f32_e32 v189, 0xbfb8aa3b, v119
	v_mul_f32_e32 v191, 0xbfb8aa3b, v120
	v_mul_f32_e32 v192, 0xbfb8aa3b, v121
	v_exp_f32_e32 v188, v188
	v_exp_f32_e32 v189, v189
	v_exp_f32_e32 v191, v191
	v_exp_f32_e32 v192, v192
	v_pk_mul_f32 v[128:129], v[128:129], v[186:187] op_sel_hi:[1,0]
	v_pk_mul_f32 v[126:127], v[126:127], v[186:187] op_sel_hi:[1,0]
	v_pk_mul_f32 v[122:123], v[122:123], v[186:187] op_sel_hi:[1,0]
	v_pk_mul_f32 v[124:125], v[124:125], v[186:187] op_sel_hi:[1,0]
	v_mul_f32_e32 v187, 0xbfb8aa3b, v129
	v_exp_f32_e32 v187, v187
	v_add_f32_e32 v194, 1.0, v188
	v_add_f32_e32 v195, 1.0, v189
	v_add_f32_e32 v191, 1.0, v191
	v_add_f32_e32 v197, 1.0, v192
	v_rcp_f32_e32 v194, v194
	v_rcp_f32_e32 v195, v195
	v_rcp_f32_e32 v196, v191
	v_rcp_f32_e32 v197, v197
	v_add_f32_e32 v187, 1.0, v187
	v_pk_mul_f32 v[118:119], v[118:119], v[194:195]
	v_pk_mul_f32 v[114:115], v[114:115], v[186:187] op_sel_hi:[1,0]
	v_pk_mul_f32 v[116:117], v[116:117], v[186:187] op_sel_hi:[1,0]
	v_pk_mul_f32 v[118:119], v[114:115], v[118:119]
	v_pk_mul_f32 v[114:115], v[120:121], v[196:197]
	v_cmp_gt_f32_e32 vcc, s83, v190
	v_pk_mul_f32 v[120:121], v[116:117], v[114:115]
	v_mul_f32_e32 v117, 0x4b800000, v190
	v_cndmask_b32_e32 v117, v190, v117, vcc
	v_mul_f32_e32 v171, 0xbfb8aa3b, v126
	v_mul_f32_e32 v173, 0xbfb8aa3b, v127
	v_mul_f32_e32 v177, 0xbfb8aa3b, v128
	v_cvt_pk_bf16_f32 v116, v118, v119
	v_rsq_f32_e32 v118, v117
	v_exp_f32_e32 v171, v171
	v_exp_f32_e32 v173, v173
	v_exp_f32_e32 v177, v177
	v_mul_f32_e32 v119, 0x45800000, v118
	v_add_f32_e32 v171, 1.0, v171
	v_add_f32_e32 v173, 1.0, v173
	v_add_f32_e32 v177, 1.0, v177
	v_cndmask_b32_e32 v118, v118, v119, vcc
	v_rcp_f32_e32 v188, v171
	v_rcp_f32_e32 v189, v173
	v_rcp_f32_e32 v192, v177
	v_rcp_f32_e32 v193, v187
	v_pk_mul_f32 v[110:111], v[110:111], v[118:119] op_sel_hi:[1,0]
	v_pk_mul_f32 v[126:127], v[126:127], v[188:189]
	v_mul_f32_e32 v119, 0xbfb8aa3b, v110
	v_exp_f32_e32 v119, v119
; #define wt16(p, v) wt16b(WSB, (p), (v))
; __device__ __forceinline__ u32x4 pack8(const float (&f)[8]) { u32x4 v; v.x = cvt_pk_bf16(f[0], f[1]); v.y = cvt_pk_bf16(f[2], f[3]); v.z = cvt_pk_bf16(f[4], f[5]); v.w = cvt_pk_bf16(f[6], f[7]); return v; }
; __device__ __forceinline__ float silu_f(float x) { return x * __builtin_amdgcn_rcpf(1.f + __expf(-x)); }
; __device__ __forceinline__ float sum4q(const f32x4 a) { return (a[0] + a[1]) + (a[2] + a[3]); }
;     __device__ __forceinline__ void operator()(const f32x4 (&acc)[2][2][4][2], const pg8::Unit& u, int wr, int wc, int fr, int fq) const {
;     ...
;         for (int ai = 0; ai < 2; ++ai)
; #pragma unroll
;             for (int m = 0; m < 4; ++m) {
;                 const int row = row0 + ai * 128 + m * 16;
;                 float ssq = sum4q(rq[ai][m]); ssq += __shfl_xor(ssq, 16); ssq += __shfl_xor(ssq, 32);
;                 const float r = rsqrtf(ssq * (1.f / DM) + EPS);
;                 float h[8];
; #pragma unroll
;                 for (int n = 0; n < 2; ++n)
; #pragma unroll
;                     for (int i = 0; i < 4; ++i) h[4 * n + i] = silu_f(acc[ai][0][m][n][i] * r) * (acc[ai][1][m][n][i] * r);
;                 wt16(H + (size_t)row * HLD + col0, pack8(h));
	v_pk_mul_f32 v[128:129], v[128:129], v[192:193]
	v_pk_mul_f32 v[122:123], v[122:123], v[126:127]
	v_pk_mul_f32 v[124:125], v[124:125], v[128:129]
	v_cvt_pk_bf16_f32 v114, v122, v123
	v_cvt_pk_bf16_f32 v115, v124, v125
	v_cvt_pk_bf16_f32 v117, v120, v121
	v_mul_f32_e32 v120, 0xbfb8aa3b, v111
	v_pk_mul_f32 v[112:113], v[112:113], v[118:119] op_sel_hi:[1,0]
	v_exp_f32_e32 v120, v120
	buffer_store_dwordx4 v[114:117], v169, s[56:59], 0 offen sc1
	v_pk_mul_f32 v[106:107], v[106:107], v[118:119] op_sel_hi:[1,0]
	v_pk_mul_f32 v[102:103], v[102:103], v[118:119] op_sel_hi:[1,0]
	v_mul_f32_e32 v116, 0xbfb8aa3b, v112
	v_mul_f32_e32 v117, 0xbfb8aa3b, v113
	v_exp_f32_e32 v116, v116
	v_exp_f32_e32 v117, v117
	v_add_f32_e32 v114, 1.0, v119
	v_add_f32_e32 v115, 1.0, v120
	v_rcp_f32_e32 v114, v114
	v_rcp_f32_e32 v115, v115
	v_add_f32_e32 v116, 1.0, v116
	v_add_f32_e32 v117, 1.0, v117
	v_rcp_f32_e32 v116, v116
	v_rcp_f32_e32 v117, v117
	v_pk_mul_f32 v[110:111], v[110:111], v[114:115]
	v_pk_mul_f32 v[108:109], v[108:109], v[118:119] op_sel_hi:[1,0]
	v_pk_mul_f32 v[106:107], v[106:107], v[110:111]
	v_pk_mul_f32 v[110:111], v[112:113], v[116:117]
	v_mul_f32_e32 v112, 0xbfb8aa3b, v102
	v_mul_f32_e32 v113, 0xbfb8aa3b, v103
	v_exp_f32_e32 v112, v112
	v_exp_f32_e32 v113, v113
	v_pk_mul_f32 v[104:105], v[104:105], v[118:119] op_sel_hi:[1,0]
	v_pk_mul_f32 v[108:109], v[108:109], v[110:111]
	v_add_f32_e32 v110, 1.0, v112
	v_add_f32_e32 v111, 1.0, v113
	v_mul_f32_e32 v112, 0xbfb8aa3b, v104
	v_mul_f32_e32 v113, 0xbfb8aa3b, v105
	v_exp_f32_e32 v112, v112
	v_exp_f32_e32 v113, v113
	v_rcp_f32_e32 v110, v110
	v_rcp_f32_e32 v111, v111
	v_add_f32_e32 v112, 1.0, v112
	v_add_f32_e32 v113, 1.0, v113
	v_rcp_f32_e32 v112, v112
	v_rcp_f32_e32 v113, v113
	v_pk_mul_f32 v[102:103], v[102:103], v[110:111]
	v_pk_mul_f32 v[98:99], v[98:99], v[118:119] op_sel_hi:[1,0]
	s_waitcnt vmcnt(5)
	v_mov_b32_e32 v110, v147
	v_pk_mul_f32 v[102:103], v[98:99], v[102:103]
	v_pk_mul_f32 v[98:99], v[104:105], v[112:113]
	v_mov_b32_e32 v104, v183
	v_mov_b32_e32 v105, v184
	v_mov_b32_e32 v183, v185
	v_mov_b32_e32 v111, v148
	v_mov_b32_e32 v147, v149
	v_pk_add_f32 v[104:105], v[104:105], v[182:183]
	v_pk_add_f32 v[110:111], v[110:111], v[146:147]
	v_mov_b32_e32 v113, v104
	v_mov_b32_e32 v112, v110
	v_mov_b32_e32 v104, v111
	v_pk_add_f32 v[104:105], v[112:113], v[104:105]
	ds_bpermute_b32 v111, v165, v105
	ds_bpermute_b32 v110, v165, v104
	v_pk_mul_f32 v[100:101], v[100:101], v[118:119] op_sel_hi:[1,0]
	s_waitcnt lgkmcnt(0)
	v_pk_add_f32 v[104:105], v[104:105], v[110:111]
	v_pk_mul_f32 v[112:113], v[100:101], v[98:99]
	v_lshlrev_b32_e32 v98, 13, v174
	v_add3_u32 v114, s70, v98, v175
	v_cvt_pk_bf16_f32 v98, v106, v107
	ds_bpermute_b32 v107, v163, v105
	ds_bpermute_b32 v106, v163, v104
	v_cvt_pk_bf16_f32 v100, v102, v103
	v_cvt_pk_bf16_f32 v99, v108, v109
	v_cvt_pk_bf16_f32 v101, v112, v113
	v_subrev_u32_e32 v108, s66, v114
	s_waitcnt lgkmcnt(0)
	v_pk_add_f32 v[102:103], v[104:105], v[106:107]
	buffer_store_dwordx4 v[98:101], v108, s[56:59], 0 offen sc1
	v_pk_fma_f32 v[102:103], v[102:103], s[2:3], v[166:167] op_sel_hi:[1,0,0]
	s_nop 0
	v_mul_f32_e32 v104, 0x4b800000, v103
	v_cmp_gt_f32_e32 vcc, s83, v103
	v_lshlrev_b32_e32 v98, 13, v176
	v_add3_u32 v99, s70, v98, v175
	v_cndmask_b32_e32 v103, v103, v104, vcc
	v_rsq_f32_e32 v103, v103
	s_nop 0
	v_mul_f32_e32 v98, 0x45800000, v103
	v_cndmask_b32_e32 v98, v103, v98, vcc
	v_pk_mul_f32 v[94:95], v[94:95], v[98:99] op_sel_hi:[1,0]
	v_subrev_u32_e32 v99, s66, v99
	v_pk_mul_f32 v[96:97], v[96:97], v[98:99] op_sel_hi:[1,0]
	v_mul_f32_e32 v100, 0xbfb8aa3b, v94
	v_mul_f32_e32 v101, 0xbfb8aa3b, v95
	v_mul_f32_e32 v103, 0xbfb8aa3b, v96
	v_exp_f32_e32 v100, v100
	v_exp_f32_e32 v101, v101
	v_exp_f32_e32 v103, v103
	v_mul_f32_e32 v104, 0xbfb8aa3b, v97
	v_exp_f32_e32 v105, v104
	v_add_f32_e32 v100, 1.0, v100
	v_add_f32_e32 v101, 1.0, v101
	v_add_f32_e32 v103, 1.0, v103
	v_rcp_f32_e32 v100, v100
	v_rcp_f32_e32 v101, v101
	v_rcp_f32_e32 v104, v103
	v_add_f32_e32 v103, 1.0, v105
	v_rcp_f32_e32 v105, v103
	v_pk_mul_f32 v[94:95], v[94:95], v[100:101]
	v_pk_mul_f32 v[90:91], v[90:91], v[98:99] op_sel_hi:[1,0]
	v_pk_mul_f32 v[86:87], v[86:87], v[98:99] op_sel_hi:[1,0]
	v_pk_mul_f32 v[90:91], v[90:91], v[94:95]
	v_pk_mul_f32 v[94:95], v[96:97], v[104:105]
	v_mul_f32_e32 v96, 0xbfb8aa3b, v86
	v_mul_f32_e32 v97, 0xbfb8aa3b, v87
	v_exp_f32_e32 v96, v96
	v_exp_f32_e32 v97, v97
	v_pk_mul_f32 v[92:93], v[92:93], v[98:99] op_sel_hi:[1,0]
	v_pk_mul_f32 v[88:89], v[88:89], v[98:99] op_sel_hi:[1,0]
	v_pk_mul_f32 v[92:93], v[92:93], v[94:95]
	v_add_f32_e32 v94, 1.0, v96
	v_add_f32_e32 v95, 1.0, v97
	v_mul_f32_e32 v96, 0xbfb8aa3b, v88
	v_mul_f32_e32 v97, 0xbfb8aa3b, v89
	v_exp_f32_e32 v96, v96
	v_exp_f32_e32 v97, v97
	v_rcp_f32_e32 v94, v94
	v_rcp_f32_e32 v95, v95
	v_add_f32_e32 v96, 1.0, v96
	v_add_f32_e32 v97, 1.0, v97
	v_rcp_f32_e32 v96, v96
	v_rcp_f32_e32 v97, v97
	v_pk_mul_f32 v[86:87], v[86:87], v[94:95]
	v_pk_mul_f32 v[82:83], v[82:83], v[98:99] op_sel_hi:[1,0]
	v_pk_mul_f32 v[84:85], v[84:85], v[98:99] op_sel_hi:[1,0]
	v_pk_mul_f32 v[86:87], v[82:83], v[86:87]
	v_pk_mul_f32 v[82:83], v[88:89], v[96:97]
	v_cmp_gt_f32_e32 vcc, s83, v102
	v_pk_mul_f32 v[88:89], v[84:85], v[82:83]
	v_mul_f32_e32 v83, 0x4b800000, v102
	v_cndmask_b32_e32 v83, v102, v83, vcc
	v_cvt_pk_bf16_f32 v82, v90, v91
	v_rsq_f32_e32 v90, v83
	v_cvt_pk_bf16_f32 v84, v86, v87
	v_cvt_pk_bf16_f32 v83, v92, v93
	v_cvt_pk_bf16_f32 v85, v88, v89
	v_mul_f32_e32 v86, 0x45800000, v90
	v_cndmask_b32_e32 v86, v90, v86, vcc
	v_pk_mul_f32 v[78:79], v[78:79], v[86:87] op_sel_hi:[1,0]
	buffer_store_dwordx4 v[82:85], v99, s[56:59], 0 offen sc1
; #define wt16(p, v) wt16b(WSB, (p), (v))
; __device__ __forceinline__ u32x4 pack8(const float (&f)[8]) { u32x4 v; v.x = cvt_pk_bf16(f[0], f[1]); v.y = cvt_pk_bf16(f[2], f[3]); v.z = cvt_pk_bf16(f[4], f[5]); v.w = cvt_pk_bf16(f[6], f[7]); return v; }
; __device__ __forceinline__ float silu_f(float x) { return x * __builtin_amdgcn_rcpf(1.f + __expf(-x)); }
; __device__ __forceinline__ float sum4q(const f32x4 a) { return (a[0] + a[1]) + (a[2] + a[3]); }
;     __device__ __forceinline__ void operator()(const f32x4 (&acc)[2][2][4][2], const pg8::Unit& u, int wr, int wc, int fr, int fq) const {
;     ...
;         for (int ai = 0; ai < 2; ++ai)
; #pragma unroll
;             for (int m = 0; m < 4; ++m) {
;                 const int row = row0 + ai * 128 + m * 16;
;                 float ssq = sum4q(rq[ai][m]); ssq += __shfl_xor(ssq, 16); ssq += __shfl_xor(ssq, 32);
;                 const float r = rsqrtf(ssq * (1.f / DM) + EPS);
;                 float h[8];
; #pragma unroll
;                 for (int n = 0; n < 2; ++n)
; #pragma unroll
;                     for (int i = 0; i < 4; ++i) h[4 * n + i] = silu_f(acc[ai][0][m][n][i] * r) * (acc[ai][1][m][n][i] * r);
;                 wt16(H + (size_t)row * HLD + col0, pack8(h));
	v_mul_f32_e32 v87, 0xbfb8aa3b, v78
	v_exp_f32_e32 v87, v87
	v_mul_f32_e32 v88, 0xbfb8aa3b, v79
	v_exp_f32_e32 v88, v88
	v_pk_mul_f32 v[80:81], v[80:81], v[86:87] op_sel_hi:[1,0]
	s_nop 0
	v_mul_f32_e32 v84, 0xbfb8aa3b, v80
	v_mul_f32_e32 v85, 0xbfb8aa3b, v81
	v_exp_f32_e32 v84, v84
	v_exp_f32_e32 v85, v85
	v_add_f32_e32 v82, 1.0, v87
	v_add_f32_e32 v83, 1.0, v88
	v_rcp_f32_e32 v82, v82
	v_rcp_f32_e32 v83, v83
	v_add_f32_e32 v84, 1.0, v84
	v_add_f32_e32 v85, 1.0, v85
	v_rcp_f32_e32 v84, v84
	v_rcp_f32_e32 v85, v85
	v_pk_mul_f32 v[78:79], v[78:79], v[82:83]
	v_pk_mul_f32 v[74:75], v[74:75], v[86:87] op_sel_hi:[1,0]
	v_pk_mul_f32 v[70:71], v[70:71], v[86:87] op_sel_hi:[1,0]
	v_pk_mul_f32 v[74:75], v[74:75], v[78:79]
	v_pk_mul_f32 v[78:79], v[80:81], v[84:85]
	v_mul_f32_e32 v80, 0xbfb8aa3b, v70
	v_mul_f32_e32 v81, 0xbfb8aa3b, v71
	v_exp_f32_e32 v80, v80
	v_exp_f32_e32 v81, v81
	v_pk_mul_f32 v[76:77], v[76:77], v[86:87] op_sel_hi:[1,0]
	v_pk_mul_f32 v[72:73], v[72:73], v[86:87] op_sel_hi:[1,0]
	v_pk_mul_f32 v[76:77], v[76:77], v[78:79]
	v_add_f32_e32 v78, 1.0, v80
	v_add_f32_e32 v79, 1.0, v81
	v_mul_f32_e32 v80, 0xbfb8aa3b, v72
	v_mul_f32_e32 v81, 0xbfb8aa3b, v73
	v_exp_f32_e32 v80, v80
	v_exp_f32_e32 v81, v81
	v_rcp_f32_e32 v78, v78
	v_rcp_f32_e32 v79, v79
	v_add_f32_e32 v80, 1.0, v80
	v_add_f32_e32 v81, 1.0, v81
	v_rcp_f32_e32 v80, v80
	v_rcp_f32_e32 v81, v81
	v_pk_mul_f32 v[70:71], v[70:71], v[78:79]
	v_pk_mul_f32 v[66:67], v[66:67], v[86:87] op_sel_hi:[1,0]
	s_waitcnt vmcnt(5)
	v_mov_b32_e32 v78, v139
	v_pk_mul_f32 v[70:71], v[66:67], v[70:71]
	v_pk_mul_f32 v[66:67], v[72:73], v[80:81]
	v_mov_b32_e32 v72, v143
	v_mov_b32_e32 v73, v144
	v_mov_b32_e32 v143, v145
	v_mov_b32_e32 v79, v140
	v_mov_b32_e32 v139, v141
	v_pk_add_f32 v[72:73], v[72:73], v[142:143]
	v_pk_add_f32 v[78:79], v[78:79], v[138:139]
	v_mov_b32_e32 v81, v72
	v_mov_b32_e32 v80, v78
	v_mov_b32_e32 v72, v79
	v_pk_add_f32 v[72:73], v[80:81], v[72:73]
	ds_bpermute_b32 v79, v165, v73
	ds_bpermute_b32 v78, v165, v72
	v_pk_mul_f32 v[68:69], v[68:69], v[86:87] op_sel_hi:[1,0]
	s_waitcnt lgkmcnt(0)
	v_pk_add_f32 v[72:73], v[72:73], v[78:79]
	v_pk_mul_f32 v[80:81], v[68:69], v[66:67]
	v_lshlrev_b32_e32 v66, 13, v172
	v_add3_u32 v82, s70, v66, v175
	v_cvt_pk_bf16_f32 v66, v74, v75
	ds_bpermute_b32 v75, v163, v73
	ds_bpermute_b32 v74, v163, v72
	v_cvt_pk_bf16_f32 v68, v70, v71
	v_cvt_pk_bf16_f32 v67, v76, v77
	v_cvt_pk_bf16_f32 v69, v80, v81
	v_subrev_u32_e32 v76, s66, v82
	s_waitcnt lgkmcnt(0)
	v_pk_add_f32 v[70:71], v[72:73], v[74:75]
	buffer_store_dwordx4 v[66:69], v76, s[56:59], 0 offen sc1
	v_pk_fma_f32 v[70:71], v[70:71], s[2:3], v[166:167] op_sel_hi:[1,0,0]
	s_nop 0
	v_mul_f32_e32 v72, 0x4b800000, v71
	v_cmp_gt_f32_e32 vcc, s83, v71
	v_lshlrev_b32_e32 v66, 13, v170
	v_add3_u32 v67, s70, v66, v175
	v_cndmask_b32_e32 v71, v71, v72, vcc
	v_rsq_f32_e32 v71, v71
	s_nop 0
	v_mul_f32_e32 v66, 0x45800000, v71
	v_cndmask_b32_e32 v66, v71, v66, vcc
	v_pk_mul_f32 v[62:63], v[62:63], v[66:67] op_sel_hi:[1,0]
	v_subrev_u32_e32 v67, s66, v67
	v_pk_mul_f32 v[64:65], v[64:65], v[66:67] op_sel_hi:[1,0]
	v_mul_f32_e32 v68, 0xbfb8aa3b, v62
	v_mul_f32_e32 v69, 0xbfb8aa3b, v63
	v_mul_f32_e32 v71, 0xbfb8aa3b, v64
	v_exp_f32_e32 v68, v68
	v_exp_f32_e32 v69, v69
	v_exp_f32_e32 v71, v71
	v_mul_f32_e32 v72, 0xbfb8aa3b, v65
	v_exp_f32_e32 v73, v72
	v_add_f32_e32 v68, 1.0, v68
	v_add_f32_e32 v69, 1.0, v69
	v_add_f32_e32 v71, 1.0, v71
	v_rcp_f32_e32 v68, v68
	v_rcp_f32_e32 v69, v69
	v_rcp_f32_e32 v72, v71
	v_add_f32_e32 v71, 1.0, v73
	v_rcp_f32_e32 v73, v71
	v_pk_mul_f32 v[62:63], v[62:63], v[68:69]
	v_pk_mul_f32 v[58:59], v[58:59], v[66:67] op_sel_hi:[1,0]
	v_pk_mul_f32 v[54:55], v[54:55], v[66:67] op_sel_hi:[1,0]
	v_pk_mul_f32 v[58:59], v[58:59], v[62:63]
	v_pk_mul_f32 v[62:63], v[64:65], v[72:73]
	v_mul_f32_e32 v64, 0xbfb8aa3b, v54
	v_mul_f32_e32 v65, 0xbfb8aa3b, v55
	v_exp_f32_e32 v64, v64
	v_exp_f32_e32 v65, v65
	v_pk_mul_f32 v[60:61], v[60:61], v[66:67] op_sel_hi:[1,0]
	v_pk_mul_f32 v[56:57], v[56:57], v[66:67] op_sel_hi:[1,0]
	v_pk_mul_f32 v[60:61], v[60:61], v[62:63]
	v_add_f32_e32 v62, 1.0, v64
	v_add_f32_e32 v63, 1.0, v65
	v_mul_f32_e32 v64, 0xbfb8aa3b, v56
	v_mul_f32_e32 v65, 0xbfb8aa3b, v57
	v_exp_f32_e32 v64, v64
	v_exp_f32_e32 v65, v65
	v_rcp_f32_e32 v62, v62
	v_rcp_f32_e32 v63, v63
	v_add_f32_e32 v64, 1.0, v64
	v_add_f32_e32 v65, 1.0, v65
	v_rcp_f32_e32 v64, v64
	v_rcp_f32_e32 v65, v65
	v_pk_mul_f32 v[54:55], v[54:55], v[62:63]
	v_pk_mul_f32 v[50:51], v[50:51], v[66:67] op_sel_hi:[1,0]
	v_pk_mul_f32 v[52:53], v[52:53], v[66:67] op_sel_hi:[1,0]
	v_pk_mul_f32 v[54:55], v[50:51], v[54:55]
	v_pk_mul_f32 v[50:51], v[56:57], v[64:65]
	v_cmp_gt_f32_e32 vcc, s83, v70
	v_pk_mul_f32 v[56:57], v[52:53], v[50:51]
	v_mul_f32_e32 v51, 0x4b800000, v70
	v_cndmask_b32_e32 v51, v70, v51, vcc
	v_cvt_pk_bf16_f32 v50, v58, v59
	v_rsq_f32_e32 v58, v51
	v_cvt_pk_bf16_f32 v52, v54, v55
	v_cvt_pk_bf16_f32 v51, v60, v61
	v_cvt_pk_bf16_f32 v53, v56, v57
	v_mul_f32_e32 v54, 0x45800000, v58
	v_cndmask_b32_e32 v54, v58, v54, vcc
	v_pk_mul_f32 v[46:47], v[46:47], v[54:55] op_sel_hi:[1,0]
	buffer_store_dwordx4 v[50:53], v67, s[56:59], 0 offen sc1
	v_mul_f32_e32 v55, 0xbfb8aa3b, v46
	v_exp_f32_e32 v55, v55
	v_mul_f32_e32 v56, 0xbfb8aa3b, v47
	v_exp_f32_e32 v56, v56
	v_pk_mul_f32 v[48:49], v[48:49], v[54:55] op_sel_hi:[1,0]
	s_nop 0
	v_mul_f32_e32 v52, 0xbfb8aa3b, v48
	v_mul_f32_e32 v53, 0xbfb8aa3b, v49
	v_exp_f32_e32 v52, v52
	v_exp_f32_e32 v53, v53
	v_add_f32_e32 v50, 1.0, v55
	v_add_f32_e32 v51, 1.0, v56
	v_rcp_f32_e32 v50, v50
	v_rcp_f32_e32 v51, v51
	v_add_f32_e32 v52, 1.0, v52
	v_add_f32_e32 v53, 1.0, v53
	v_rcp_f32_e32 v52, v52
	v_rcp_f32_e32 v53, v53
	v_pk_mul_f32 v[46:47], v[46:47], v[50:51]
	v_pk_mul_f32 v[42:43], v[42:43], v[54:55] op_sel_hi:[1,0]
	v_pk_mul_f32 v[38:39], v[38:39], v[54:55] op_sel_hi:[1,0]
	v_pk_mul_f32 v[42:43], v[42:43], v[46:47]
	v_pk_mul_f32 v[46:47], v[48:49], v[52:53]
	v_mul_f32_e32 v48, 0xbfb8aa3b, v38
	v_mul_f32_e32 v49, 0xbfb8aa3b, v39
	v_exp_f32_e32 v48, v48
	v_exp_f32_e32 v49, v49
	v_pk_mul_f32 v[44:45], v[44:45], v[54:55] op_sel_hi:[1,0]
	v_pk_mul_f32 v[40:41], v[40:41], v[54:55] op_sel_hi:[1,0]
	v_pk_mul_f32 v[44:45], v[44:45], v[46:47]
	v_add_f32_e32 v46, 1.0, v48
	v_add_f32_e32 v47, 1.0, v49
	v_mul_f32_e32 v48, 0xbfb8aa3b, v40
	v_mul_f32_e32 v49, 0xbfb8aa3b, v41
	v_exp_f32_e32 v48, v48
	v_exp_f32_e32 v49, v49
	v_rcp_f32_e32 v46, v46
	v_rcp_f32_e32 v47, v47
	v_add_f32_e32 v48, 1.0, v48
	v_add_f32_e32 v49, 1.0, v49
	v_rcp_f32_e32 v48, v48
	v_rcp_f32_e32 v49, v49
	v_pk_mul_f32 v[38:39], v[38:39], v[46:47]
	v_pk_mul_f32 v[34:35], v[34:35], v[54:55] op_sel_hi:[1,0]
	s_waitcnt vmcnt(5)
; #define PG8_BAR __builtin_amdgcn_s_barrier()
; #define wt16(p, v) wt16b(WSB, (p), (v))
; __device__ __forceinline__ u32x4 pack8(const float (&f)[8]) { u32x4 v; v.x = cvt_pk_bf16(f[0], f[1]); v.y = cvt_pk_bf16(f[2], f[3]); v.z = cvt_pk_bf16(f[4], f[5]); v.w = cvt_pk_bf16(f[6], f[7]); return v; }
; __device__ __forceinline__ float silu_f(float x) { return x * __builtin_amdgcn_rcpf(1.f + __expf(-x)); }
; __device__ __forceinline__ float sum4q(const f32x4 a) { return (a[0] + a[1]) + (a[2] + a[3]); }
; template <class Epi, class Sched, bool ALIGN_EPI>
; __device__ __forceinline__ void gemm_phase(PG8_LAS unsigned char* lds, const Gemm g, const Sched& S, const Epi& E) {
;     ...
;         E(acc, cur, wr, wc, fr, fq);
;         if (!has_next) break;
; #pragma unroll
;         for (int a = 0; a < 2; ++a)
; #pragma unroll
;             for (int b = 0; b < 2; ++b)
; #pragma unroll
;                 for (int m = 0; m < 4; ++m)
; #pragma unroll
;                     for (int n = 0; n < 2; ++n) acc[a][b][m][n] = (f32x4){0.f, 0.f, 0.f, 0.f};
;         cur = nxt; cA = nA; cB = nB; ++ui;
;         if constexpr (ALIGN_EPI) { if (wr == 1) PG8_BAR; }
;     }
;     __device__ __forceinline__ void operator()(const f32x4 (&acc)[2][2][4][2], const pg8::Unit& u, int wr, int wc, int fr, int fq) const {
;     ...
;         for (int ai = 0; ai < 2; ++ai)
; #pragma unroll
;             for (int m = 0; m < 4; ++m) {
;                 const int row = row0 + ai * 128 + m * 16;
;                 float ssq = sum4q(rq[ai][m]); ssq += __shfl_xor(ssq, 16); ssq += __shfl_xor(ssq, 32);
;                 const float r = rsqrtf(ssq * (1.f / DM) + EPS);
;                 float h[8];
; #pragma unroll
;                 for (int n = 0; n < 2; ++n)
; #pragma unroll
;                     for (int i = 0; i < 4; ++i) h[4 * n + i] = silu_f(acc[ai][0][m][n][i] * r) * (acc[ai][1][m][n][i] * r);
;                 wt16(H + (size_t)row * HLD + col0, pack8(h));
;             }
	v_mov_b32_e32 v46, v131
	v_pk_mul_f32 v[38:39], v[34:35], v[38:39]
	v_pk_mul_f32 v[34:35], v[40:41], v[48:49]
	v_mov_b32_e32 v40, v135
	v_mov_b32_e32 v41, v136
	v_mov_b32_e32 v135, v137
	v_mov_b32_e32 v47, v132
	v_mov_b32_e32 v131, v133
	v_pk_add_f32 v[40:41], v[40:41], v[134:135]
	v_pk_add_f32 v[46:47], v[46:47], v[130:131]
	v_mov_b32_e32 v49, v40
	v_mov_b32_e32 v48, v46
	v_mov_b32_e32 v40, v47
	v_pk_add_f32 v[40:41], v[48:49], v[40:41]
	ds_bpermute_b32 v47, v165, v41
	ds_bpermute_b32 v46, v165, v40
	v_pk_mul_f32 v[36:37], v[36:37], v[54:55] op_sel_hi:[1,0]
	s_waitcnt lgkmcnt(0)
	v_pk_add_f32 v[40:41], v[40:41], v[46:47]
	v_pk_mul_f32 v[48:49], v[36:37], v[34:35]
	v_lshlrev_b32_e32 v34, 13, v168
	v_add3_u32 v50, s70, v34, v175
	v_cvt_pk_bf16_f32 v34, v42, v43
	ds_bpermute_b32 v43, v163, v41
	ds_bpermute_b32 v42, v163, v40
	v_cvt_pk_bf16_f32 v36, v38, v39
	v_cvt_pk_bf16_f32 v35, v44, v45
	v_cvt_pk_bf16_f32 v37, v48, v49
	v_subrev_u32_e32 v44, s66, v50
	s_waitcnt lgkmcnt(0)
	v_pk_add_f32 v[38:39], v[40:41], v[42:43]
	buffer_store_dwordx4 v[34:37], v44, s[56:59], 0 offen sc1
	v_pk_fma_f32 v[38:39], v[38:39], s[2:3], v[166:167] op_sel_hi:[1,0,0]
	s_mov_b64 s[2:3], -1
	v_mul_f32_e32 v40, 0x4b800000, v39
	v_cmp_gt_f32_e32 vcc, s83, v39
	v_lshlrev_b32_e32 v34, 13, v164
	v_add3_u32 v35, s70, v34, v175
	v_cndmask_b32_e32 v39, v39, v40, vcc
	v_rsq_f32_e32 v39, v39
	s_nop 0
	v_mul_f32_e32 v34, 0x45800000, v39
	v_cndmask_b32_e32 v34, v39, v34, vcc
	v_pk_mul_f32 v[30:31], v[30:31], v[34:35] op_sel_hi:[1,0]
	v_subrev_u32_e32 v35, s66, v35
	v_pk_mul_f32 v[32:33], v[32:33], v[34:35] op_sel_hi:[1,0]
	v_mul_f32_e32 v36, 0xbfb8aa3b, v30
	v_mul_f32_e32 v37, 0xbfb8aa3b, v31
	v_mul_f32_e32 v39, 0xbfb8aa3b, v32
	v_exp_f32_e32 v36, v36
	v_exp_f32_e32 v37, v37
	v_exp_f32_e32 v39, v39
	v_mul_f32_e32 v40, 0xbfb8aa3b, v33
	v_exp_f32_e32 v41, v40
	v_add_f32_e32 v36, 1.0, v36
	v_add_f32_e32 v37, 1.0, v37
	v_add_f32_e32 v39, 1.0, v39
	v_rcp_f32_e32 v36, v36
	v_rcp_f32_e32 v37, v37
	v_rcp_f32_e32 v40, v39
	v_add_f32_e32 v39, 1.0, v41
	v_rcp_f32_e32 v41, v39
	v_pk_mul_f32 v[30:31], v[30:31], v[36:37]
	v_pk_mul_f32 v[26:27], v[26:27], v[34:35] op_sel_hi:[1,0]
	v_pk_mul_f32 v[22:23], v[22:23], v[34:35] op_sel_hi:[1,0]
	v_pk_mul_f32 v[26:27], v[26:27], v[30:31]
	v_pk_mul_f32 v[30:31], v[32:33], v[40:41]
	v_mul_f32_e32 v32, 0xbfb8aa3b, v22
	v_mul_f32_e32 v33, 0xbfb8aa3b, v23
	v_exp_f32_e32 v32, v32
	v_exp_f32_e32 v33, v33
	v_pk_mul_f32 v[28:29], v[28:29], v[34:35] op_sel_hi:[1,0]
	v_pk_mul_f32 v[24:25], v[24:25], v[34:35] op_sel_hi:[1,0]
	v_pk_mul_f32 v[28:29], v[28:29], v[30:31]
	v_add_f32_e32 v30, 1.0, v32
	v_add_f32_e32 v31, 1.0, v33
	v_mul_f32_e32 v32, 0xbfb8aa3b, v24
	v_mul_f32_e32 v33, 0xbfb8aa3b, v25
	v_exp_f32_e32 v32, v32
	v_exp_f32_e32 v33, v33
	v_rcp_f32_e32 v30, v30
	v_rcp_f32_e32 v31, v31
	v_add_f32_e32 v32, 1.0, v32
	v_add_f32_e32 v33, 1.0, v33
	v_rcp_f32_e32 v32, v32
	v_rcp_f32_e32 v33, v33
	v_pk_mul_f32 v[22:23], v[22:23], v[30:31]
	v_pk_mul_f32 v[18:19], v[18:19], v[34:35] op_sel_hi:[1,0]
	v_pk_mul_f32 v[20:21], v[20:21], v[34:35] op_sel_hi:[1,0]
	v_pk_mul_f32 v[22:23], v[18:19], v[22:23]
	v_pk_mul_f32 v[18:19], v[24:25], v[32:33]
	v_cmp_gt_f32_e32 vcc, s83, v38
	v_pk_mul_f32 v[24:25], v[20:21], v[18:19]
	v_mul_f32_e32 v19, 0x4b800000, v38
	v_cndmask_b32_e32 v19, v38, v19, vcc
	v_cvt_pk_bf16_f32 v18, v26, v27
	v_rsq_f32_e32 v26, v19
	v_cvt_pk_bf16_f32 v20, v22, v23
	v_cvt_pk_bf16_f32 v19, v28, v29
	v_cvt_pk_bf16_f32 v21, v24, v25
	v_mul_f32_e32 v22, 0x45800000, v26
	v_cndmask_b32_e32 v22, v26, v22, vcc
	v_pk_mul_f32 v[14:15], v[14:15], v[22:23] op_sel_hi:[1,0]
	buffer_store_dwordx4 v[18:21], v35, s[56:59], 0 offen sc1
	v_mul_f32_e32 v23, 0xbfb8aa3b, v14
	v_exp_f32_e32 v23, v23
	v_mul_f32_e32 v24, 0xbfb8aa3b, v15
	v_exp_f32_e32 v24, v24
	s_andn2_b64 vcc, exec, s[40:41]
	v_pk_mul_f32 v[16:17], v[16:17], v[22:23] op_sel_hi:[1,0]
	v_add_f32_e32 v18, 1.0, v23
	v_mul_f32_e32 v20, 0xbfb8aa3b, v16
	v_mul_f32_e32 v21, 0xbfb8aa3b, v17
	v_exp_f32_e32 v20, v20
	v_exp_f32_e32 v21, v21
	v_add_f32_e32 v19, 1.0, v24
	v_rcp_f32_e32 v18, v18
	v_rcp_f32_e32 v19, v19
	v_add_f32_e32 v20, 1.0, v20
	v_add_f32_e32 v21, 1.0, v21
	v_rcp_f32_e32 v20, v20
	v_rcp_f32_e32 v21, v21
	v_pk_mul_f32 v[14:15], v[14:15], v[18:19]
	v_pk_mul_f32 v[10:11], v[10:11], v[22:23] op_sel_hi:[1,0]
	v_pk_mul_f32 v[6:7], v[6:7], v[22:23] op_sel_hi:[1,0]
	v_pk_mul_f32 v[10:11], v[10:11], v[14:15]
	v_pk_mul_f32 v[14:15], v[16:17], v[20:21]
	v_mul_f32_e32 v16, 0xbfb8aa3b, v6
	v_mul_f32_e32 v17, 0xbfb8aa3b, v7
	v_exp_f32_e32 v16, v16
	v_exp_f32_e32 v17, v17
	v_pk_mul_f32 v[12:13], v[12:13], v[22:23] op_sel_hi:[1,0]
	v_pk_mul_f32 v[8:9], v[8:9], v[22:23] op_sel_hi:[1,0]
	v_pk_mul_f32 v[12:13], v[12:13], v[14:15]
	v_add_f32_e32 v14, 1.0, v16
	v_add_f32_e32 v15, 1.0, v17
	v_mul_f32_e32 v16, 0xbfb8aa3b, v8
	v_mul_f32_e32 v17, 0xbfb8aa3b, v9
	v_exp_f32_e32 v16, v16
	v_exp_f32_e32 v17, v17
	v_rcp_f32_e32 v14, v14
	v_rcp_f32_e32 v15, v15
	v_add_f32_e32 v16, 1.0, v16
	v_add_f32_e32 v17, 1.0, v17
	v_rcp_f32_e32 v16, v16
	v_rcp_f32_e32 v17, v17
	v_pk_mul_f32 v[6:7], v[6:7], v[14:15]
	v_pk_mul_f32 v[2:3], v[2:3], v[22:23] op_sel_hi:[1,0]
	v_pk_mul_f32 v[4:5], v[4:5], v[22:23] op_sel_hi:[1,0]
	v_pk_mul_f32 v[6:7], v[2:3], v[6:7]
	v_pk_mul_f32 v[2:3], v[8:9], v[16:17]
	s_nop 0
	v_pk_mul_f32 v[8:9], v[4:5], v[2:3]
	v_lshlrev_b32_e32 v2, 13, v162
	v_add3_u32 v14, s70, v2, v175
	v_cvt_pk_bf16_f32 v2, v10, v11
	v_cvt_pk_bf16_f32 v3, v12, v13
	v_cvt_pk_bf16_f32 v4, v6, v7
	v_cvt_pk_bf16_f32 v5, v8, v9
	v_subrev_u32_e32 v6, s66, v14
	buffer_store_dwordx4 v[2:5], v6, s[56:59], 0 offen sc1
	s_cbranch_vccnz .LBB0_364
	s_andn2_b64 vcc, exec, s[10:11]
	s_cbranch_vccnz .LBB0_363
	s_barrier
	s_branch .LBB0_363
